# RWKV: DPP gaps filled with operand reads, per-lane output partials summed by the reader
# baseline (speedup 1.0000x reference)
; __device__ __forceinline__ int otid() { int t = threadIdx.x; asm volatile("" : "+v"(t)); return t; }
; __device__ __forceinline__ void rwkv_item(const Params& p, int item, float* sm) {
;     ...
;   const int tid = otid(), lane = tid & 63, wave = tid >> 6;
;   const int sub = lane & 15, rowl = wave * 4 + (lane >> 4);
;   const int ltt = tid >> 4, lrr = tid & 15;
;   const int ch = h * 64 + lane;
;   const float kkw = p.k_k[ch], kaw = p.k_a[ch], rkw = p.r_k[ch];
;   const size_t rowb = (size_t)b * LP;
;   float S0 = 0.f, S1 = 0.f, S2 = 0.f, S3 = 0.f;
;   bf16_t pr0, pr1, pr2, pr3, pk0, pk1, pk2, pk3, pa0, pa1, pa2, pa3, pw0, pw1, pw2, pw3, pv;
;     ...
;   __syncthreads();
;   RW_LOAD(PADR)
;   RW_STORE(0, PADR)
;   __syncthreads();
.Lrw_yjoin:
	s_add_u32 s10, s10, s23
	s_addc_u32 s11, s11, 0
	v_readlane_b32 s24, v247, 9
	v_readlane_b32 s25, v247, 10
	v_readlane_b32 s26, v247, 11
	v_readlane_b32 s27, v247, 12
	s_lshl_b32 s23, s2, 8
	v_lshl_add_u32 v139, v137, 4, s23
	s_nop 1
	global_load_dwordx4 v[16:19], v139, s[24:25]
	global_load_dwordx4 v[20:23], v139, s[26:27]
	v_readlane_b32 s24, v247, 13
	v_readlane_b32 s25, v247, 14
	v_lshlrev_b32_e32 v47, 4, v137
	v_lshlrev_b32_e32 v136, 6, v138
	v_add_u32_e32 v136, 20480, v136
	v_lshlrev_b32_e32 v132, 4, v2
	v_lshl_add_u32 v133, v137, 4, v138
	v_lshlrev_b32_e32 v133, 2, v133
	v_add_u32_e32 v133, 20480, v133
	global_load_dwordx4 v[24:27], v139, s[24:25]
	v_mul_u32_u24_e32 v134, 0x410, v138
	v_lshl_add_u32 v134, v137, 6, v134
	v_add_u32_e32 v134, 0xb000, v134
	v_mul_u32_u24_e32 v135, 0x410, v137
	v_lshl_add_u32 v135, v138, 2, v135
	v_add_u32_e32 v135, 0xb000, v135
	v_add_u32_e32 v140, s22, v138
	s_lshl_b32 s23, s2, 7
	v_lshl_add_u32 v141, v137, 3, s23
	s_movk_i32 s19, 0x1800
	v_mad_u32_u24 v28, v140, s19, v141
	v_lshl_add_u32 v29, v140, 11, v141
	s_lshl_b32 s19, s18, 5
	s_add_i32 s19, s19, s23
	v_lshl_add_u32 v142, v137, 1, s19
	s_movk_i32 s23, 0x1800
	v_mad_u32_u24 v30, v140, s23, v142
	v_add_u32_e32 v30, 0x1000, v30
	v_add_u32_e32 v143, 0x70, v138
	v_lshl_add_u32 v31, v143, 11, v142
	s_lshl_b32 s19, s2, 4
	s_lshl_b32 s23, s18, 2
	s_add_i32 s19, s19, s23
	v_lshl_add_u32 v32, v140, 8, s19
	s_lshl_b32 s19, s2, 2
	v_lshl_add_u32 v33, v140, 6, s19
	s_mov_b32 s20, -1.0
	s_mov_b32 s21, -1.0
	s_mov_b32 s30, 1.0
	s_mov_b32 s31, 1.0
	s_mov_b32 s22, 0xbfb8aa3b
	s_mov_b32 s23, 0xbfb8aa3b
	v_mov_b32_e32 v12, 0
	v_mov_b32_e32 v13, 0
	v_mov_b32_e32 v14, 0
	v_mov_b32_e32 v15, 0
	s_barrier
	global_load_dwordx2 v[34:35], v28, s[4:5]
	global_load_dwordx2 v[36:37], v28, s[4:5] offset:2048
	global_load_dwordx2 v[38:39], v29, s[6:7]
	global_load_dwordx2 v[40:41], v29, s[8:9]
	global_load_ushort v42, v30, s[4:5]
	v_mov_b32_e32 v43, v132
	v_mov_b32_e32 v44, v133
	s_waitcnt vmcnt(0)
	v_lshlrev_b32_e32 v48, 16, v34
	v_and_b32_e32 v49, 0xffff0000, v34
	v_lshlrev_b32_e32 v50, 16, v35
	v_and_b32_e32 v51, 0xffff0000, v35
	v_lshlrev_b32_e32 v52, 16, v36
	v_and_b32_e32 v53, 0xffff0000, v36
	v_lshlrev_b32_e32 v54, 16, v37
	v_and_b32_e32 v55, 0xffff0000, v37
	v_lshlrev_b32_e32 v56, 16, v38
	v_and_b32_e32 v57, 0xffff0000, v38
	v_lshlrev_b32_e32 v58, 16, v39
	v_and_b32_e32 v59, 0xffff0000, v39
	v_lshlrev_b32_e32 v60, 16, v40
	v_and_b32_e32 v61, 0xffff0000, v40
	v_lshlrev_b32_e32 v62, 16, v41
	v_and_b32_e32 v63, 0xffff0000, v41
	v_lshlrev_b32_e32 v64, 16, v42
	v_pk_mul_f32 v[68:69], v[52:53], v[16:17]
	v_pk_mul_f32 v[70:71], v[54:55], v[18:19]
	v_pk_mul_f32 v[72:73], v[68:69], v[68:69]
	v_pk_fma_f32 v[72:73], v[70:71], v[70:71], v[72:73]
	v_pk_add_f32 v[76:77], v[56:57], s[20:21]
	v_add_f32_e32 v74, v72, v73
	v_pk_add_f32 v[78:79], v[58:59], s[20:21]
	v_pk_mul_f32 v[84:85], v[60:61], s[22:23]
	v_add_f32_dpp v74, v74, v74 quad_perm:[1,0,3,2] row_mask:0xf bank_mask:0xf bound_ctrl:1
	v_pk_mul_f32 v[86:87], v[62:63], s[22:23]
	v_pk_fma_f32 v[76:77], v[76:77], v[20:21], s[30:31]
	v_add_f32_dpp v74, v74, v74 quad_perm:[2,3,0,1] row_mask:0xf bank_mask:0xf bound_ctrl:1
	v_pk_fma_f32 v[78:79], v[78:79], v[22:23], s[30:31]
	v_exp_f32_e32 v84, v84
	v_add_f32_dpp v74, v74, v74 row_half_mirror row_mask:0xf bank_mask:0xf bound_ctrl:1
	v_exp_f32_e32 v85, v85
	v_exp_f32_e32 v86, v86
	v_add_f32_dpp v74, v74, v74 row_mirror row_mask:0xf bank_mask:0xf bound_ctrl:1
	v_exp_f32_e32 v87, v87
	v_pk_mul_f32 v[80:81], v[52:53], v[76:77]
	v_add_f32_e32 v74, 0x358637bd, v74
	v_pk_mul_f32 v[82:83], v[54:55], v[78:79]
	v_rsq_f32_e32 v120, v74
	ds_write_b128 v43, v[84:87]
	ds_write_b128 v43, v[48:51] offset:16384
	ds_write_b32 v44, v64
	ds_write_b128 v43, v[80:83] offset:4096
	v_pk_mul_f32 v[124:125], v[68:69], v[120:121] op_sel_hi:[1,0] neg_lo:[0,1] neg_hi:[0,1]
	v_pk_mul_f32 v[126:127], v[70:71], v[120:121] op_sel_hi:[1,0] neg_lo:[0,1] neg_hi:[0,1]
	v_pk_mul_f32 v[100:101], v[124:125], v[56:57] neg_lo:[1,0] neg_hi:[1,0]
	v_pk_mul_f32 v[102:103], v[126:127], v[58:59] neg_lo:[1,0] neg_hi:[1,0]
	ds_write_b128 v43, v[124:127] offset:8192
	ds_write_b128 v43, v[100:103] offset:12288
	s_cmp_lg_u32 s18, 0
	s_cbranch_scc1 .Lrw_nosb_p0
	v_pk_mul_f32 v[104:105], v[48:49], v[80:81]
	v_pk_mul_f32 v[106:107], v[50:51], v[82:83]
	v_pk_mul_f32 v[108:109], v[104:105], v[24:25]
	v_pk_fma_f32 v[108:109], v[106:107], v[26:27], v[108:109]
	v_add_f32_e32 v110, v108, v109
	s_nop 1
	v_add_f32_dpp v110, v110, v110 quad_perm:[1,0,3,2] row_mask:0xf bank_mask:0xf bound_ctrl:1
	s_nop 1
	v_add_f32_dpp v110, v110, v110 quad_perm:[2,3,0,1] row_mask:0xf bank_mask:0xf bound_ctrl:1
	s_nop 1
	v_add_f32_dpp v110, v110, v110 row_half_mirror row_mask:0xf bank_mask:0xf bound_ctrl:1
	s_nop 1
	v_add_f32_dpp v110, v110, v110 row_mirror row_mask:0xf bank_mask:0xf bound_ctrl:1
	global_store_dword v33, v110, s[16:17]

; __device__ __forceinline__ void rwkv_item(const Params& p, int item, float* sm) {
;     ...
; #pragma unroll
;       for (int t = 0; t < TC; t++) {
;         const float4 w4 = *(const float4*)(bw + 0 * TC * 64 + t * 64 + sub * 4);
;         const float4 k4 = *(const float4*)(bw + 1 * TC * 64 + t * 64 + sub * 4);
;         const float4 a4 = *(const float4*)(bw + 2 * TC * 64 + t * 64 + sub * 4);
;         const float4 b4 = *(const float4*)(bw + 3 * TC * 64 + t * 64 + sub * 4);
;         const float4 r4 = *(const float4*)(bw + 4 * TC * 64 + t * 64 + sub * 4);
;         const float v = bv[t * 16 + rowl];
;         const float sa = dpp_sum16((S0 * a4.x + S1 * a4.y) + (S2 * a4.z + S3 * a4.w));
;         S0 = (S0 * w4.x + v * k4.x) + sa * b4.x;
;         S1 = (S1 * w4.y + v * k4.y) + sa * b4.y;
;         S2 = (S2 * w4.z + v * k4.z) + sa * b4.z;
;         S3 = (S3 * w4.w + v * k4.w) + sa * b4.w;
;         yreg[t] = (S0 * r4.x + S1 * r4.y) + (S2 * r4.z + S3 * r4.w);
;       }
.Lrw_noload:
	s_waitcnt lgkmcnt(5)
	v_pk_mul_f32 v[120:121], v[12:13], v[56:57]
	v_pk_fma_f32 v[120:121], v[14:15], v[58:59], v[120:121]
	v_pk_mul_f32 v[122:123], v[12:13], v[48:49]
	v_add_f32_e32 v128, v120, v121
	v_pk_mul_f32 v[124:125], v[14:15], v[50:51]
	v_pk_fma_f32 v[122:123], v[52:53], v[88:89], v[122:123] op_sel_hi:[1,0,1]
	v_add_f32_dpp v128, v128, v128 quad_perm:[1,0,3,2] row_mask:0xf bank_mask:0xf bound_ctrl:1
	v_pk_fma_f32 v[124:125], v[54:55], v[88:89], v[124:125] op_sel_hi:[1,0,1]
	ds_read_b128 v[148:151], v10 offset:4608
	v_add_f32_dpp v128, v128, v128 quad_perm:[2,3,0,1] row_mask:0xf bank_mask:0xf bound_ctrl:1
	ds_read_b128 v[156:159], v10 offset:12800
	ds_read_b128 v[138:141], v10 offset:16896
	v_add_f32_dpp v128, v128, v128 row_half_mirror row_mask:0xf bank_mask:0xf bound_ctrl:1
	ds_read_b128 v[144:147], v10 offset:512
	ds_read_b128 v[152:155], v10 offset:8704
	v_add_f32_dpp v130, v128, v128 row_mirror row_mask:0xf bank_mask:0xf bound_ctrl:1
	v_pk_fma_f32 v[12:13], v[60:61], v[130:131], v[122:123] op_sel_hi:[1,0,1]
	v_pk_fma_f32 v[14:15], v[62:63], v[130:131], v[124:125] op_sel_hi:[1,0,1]
	v_pk_mul_f32 v[126:127], v[12:13], v[80:81]
	v_pk_fma_f32 v[126:127], v[14:15], v[82:83], v[126:127]
	s_waitcnt lgkmcnt(5)
	ds_read_b128 v[56:59], v10 offset:8960
	v_pk_mul_f32 v[120:121], v[12:13], v[72:73]
	v_pk_fma_f32 v[120:121], v[14:15], v[74:75], v[120:121]
	v_pk_mul_f32 v[122:123], v[12:13], v[64:65]
	v_add_f32_e32 v128, v120, v121
	v_pk_mul_f32 v[124:125], v[14:15], v[66:67]
	v_pk_fma_f32 v[122:123], v[68:69], v[88:89], v[122:123] op_sel:[0,1,0] op_sel_hi:[1,1,1]
	v_add_f32_dpp v128, v128, v128 quad_perm:[1,0,3,2] row_mask:0xf bank_mask:0xf bound_ctrl:1
	v_pk_fma_f32 v[124:125], v[70:71], v[88:89], v[124:125] op_sel:[0,1,0] op_sel_hi:[1,1,1]
	ds_read_b128 v[52:55], v10 offset:4864
	v_add_f32_dpp v128, v128, v128 quad_perm:[2,3,0,1] row_mask:0xf bank_mask:0xf bound_ctrl:1
	ds_read_b128 v[60:63], v10 offset:13056
	ds_read_b128 v[80:83], v10 offset:17152
	v_add_f32_dpp v128, v128, v128 row_half_mirror row_mask:0xf bank_mask:0xf bound_ctrl:1
	v_add_f32_e32 v104, v126, v127
	ds_read_b128 v[48:51], v10 offset:768
	v_add_f32_dpp v130, v128, v128 row_mirror row_mask:0xf bank_mask:0xf bound_ctrl:1
	v_pk_fma_f32 v[12:13], v[76:77], v[130:131], v[122:123] op_sel_hi:[1,0,1]
	v_pk_fma_f32 v[14:15], v[78:79], v[130:131], v[124:125] op_sel_hi:[1,0,1]
	v_pk_mul_f32 v[126:127], v[12:13], v[84:85]
	v_pk_fma_f32 v[126:127], v[14:15], v[86:87], v[126:127]
	s_waitcnt lgkmcnt(5)
	ds_read_b128 v[72:75], v10 offset:9216
	v_pk_mul_f32 v[120:121], v[12:13], v[152:153]
	v_pk_fma_f32 v[120:121], v[14:15], v[154:155], v[120:121]
	v_pk_mul_f32 v[122:123], v[12:13], v[144:145]
	v_add_f32_e32 v128, v120, v121
	v_pk_mul_f32 v[124:125], v[14:15], v[146:147]
	v_pk_fma_f32 v[122:123], v[148:149], v[90:91], v[122:123] op_sel_hi:[1,0,1]
	v_add_f32_dpp v128, v128, v128 quad_perm:[1,0,3,2] row_mask:0xf bank_mask:0xf bound_ctrl:1
	v_pk_fma_f32 v[124:125], v[150:151], v[90:91], v[124:125] op_sel_hi:[1,0,1]
	ds_read_b128 v[68:71], v10 offset:5120
	v_add_f32_dpp v128, v128, v128 quad_perm:[2,3,0,1] row_mask:0xf bank_mask:0xf bound_ctrl:1
	ds_read_b128 v[76:79], v10 offset:13312
	ds_read_b128 v[84:87], v10 offset:17408
	v_add_f32_dpp v128, v128, v128 row_half_mirror row_mask:0xf bank_mask:0xf bound_ctrl:1
	v_add_f32_e32 v105, v126, v127
	ds_read_b128 v[64:67], v10 offset:1024
	v_add_f32_dpp v130, v128, v128 row_mirror row_mask:0xf bank_mask:0xf bound_ctrl:1
	v_pk_fma_f32 v[12:13], v[156:157], v[130:131], v[122:123] op_sel_hi:[1,0,1]
	v_pk_fma_f32 v[14:15], v[158:159], v[130:131], v[124:125] op_sel_hi:[1,0,1]
	v_pk_mul_f32 v[126:127], v[12:13], v[138:139]
	v_pk_fma_f32 v[126:127], v[14:15], v[140:141], v[126:127]
	s_waitcnt lgkmcnt(5)
	ds_read_b128 v[152:155], v10 offset:9472
	v_pk_mul_f32 v[120:121], v[12:13], v[56:57]
	v_pk_fma_f32 v[120:121], v[14:15], v[58:59], v[120:121]
	v_pk_mul_f32 v[122:123], v[12:13], v[48:49]
	v_add_f32_e32 v128, v120, v121
	v_pk_mul_f32 v[124:125], v[14:15], v[50:51]
	v_pk_fma_f32 v[122:123], v[52:53], v[90:91], v[122:123] op_sel:[0,1,0] op_sel_hi:[1,1,1]
	v_add_f32_dpp v128, v128, v128 quad_perm:[1,0,3,2] row_mask:0xf bank_mask:0xf bound_ctrl:1
	v_pk_fma_f32 v[124:125], v[54:55], v[90:91], v[124:125] op_sel:[0,1,0] op_sel_hi:[1,1,1]
	ds_read_b128 v[148:151], v10 offset:5376
	v_add_f32_dpp v128, v128, v128 quad_perm:[2,3,0,1] row_mask:0xf bank_mask:0xf bound_ctrl:1
	ds_read_b128 v[156:159], v10 offset:13568
	ds_read_b128 v[138:141], v10 offset:17664
	v_add_f32_dpp v128, v128, v128 row_half_mirror row_mask:0xf bank_mask:0xf bound_ctrl:1
	v_add_f32_e32 v106, v126, v127
	ds_read_b128 v[144:147], v10 offset:1280
	v_add_f32_dpp v130, v128, v128 row_mirror row_mask:0xf bank_mask:0xf bound_ctrl:1
	v_pk_fma_f32 v[12:13], v[60:61], v[130:131], v[122:123] op_sel_hi:[1,0,1]
	v_pk_fma_f32 v[14:15], v[62:63], v[130:131], v[124:125] op_sel_hi:[1,0,1]
	v_pk_mul_f32 v[126:127], v[12:13], v[80:81]
	v_pk_fma_f32 v[126:127], v[14:15], v[82:83], v[126:127]
	s_waitcnt lgkmcnt(5)
; __device__ __forceinline__ void rwkv_item(const Params& p, int item, float* sm) {
;     ...
; #pragma unroll
;       for (int t = 0; t < TC; t++) {
;         const float4 w4 = *(const float4*)(bw + 0 * TC * 64 + t * 64 + sub * 4);
;         const float4 k4 = *(const float4*)(bw + 1 * TC * 64 + t * 64 + sub * 4);
;         const float4 a4 = *(const float4*)(bw + 2 * TC * 64 + t * 64 + sub * 4);
;         const float4 b4 = *(const float4*)(bw + 3 * TC * 64 + t * 64 + sub * 4);
;         const float4 r4 = *(const float4*)(bw + 4 * TC * 64 + t * 64 + sub * 4);
;         const float v = bv[t * 16 + rowl];
;         const float sa = dpp_sum16((S0 * a4.x + S1 * a4.y) + (S2 * a4.z + S3 * a4.w));
;         S0 = (S0 * w4.x + v * k4.x) + sa * b4.x;
;         S1 = (S1 * w4.y + v * k4.y) + sa * b4.y;
;         S2 = (S2 * w4.z + v * k4.z) + sa * b4.z;
;         S3 = (S3 * w4.w + v * k4.w) + sa * b4.w;
;         yreg[t] = (S0 * r4.x + S1 * r4.y) + (S2 * r4.z + S3 * r4.w);
;       }
	ds_read_b128 v[56:59], v10 offset:9728
	v_pk_mul_f32 v[120:121], v[12:13], v[72:73]
	v_pk_fma_f32 v[120:121], v[14:15], v[74:75], v[120:121]
	v_pk_mul_f32 v[122:123], v[12:13], v[64:65]
	v_add_f32_e32 v128, v120, v121
	v_pk_mul_f32 v[124:125], v[14:15], v[66:67]
	v_pk_fma_f32 v[122:123], v[68:69], v[92:93], v[122:123] op_sel_hi:[1,0,1]
	v_add_f32_dpp v128, v128, v128 quad_perm:[1,0,3,2] row_mask:0xf bank_mask:0xf bound_ctrl:1
	v_pk_fma_f32 v[124:125], v[70:71], v[92:93], v[124:125] op_sel_hi:[1,0,1]
	ds_read_b128 v[52:55], v10 offset:5632
	v_add_f32_dpp v128, v128, v128 quad_perm:[2,3,0,1] row_mask:0xf bank_mask:0xf bound_ctrl:1
	ds_read_b128 v[60:63], v10 offset:13824
	ds_read_b128 v[80:83], v10 offset:17920
	v_add_f32_dpp v128, v128, v128 row_half_mirror row_mask:0xf bank_mask:0xf bound_ctrl:1
	v_add_f32_e32 v107, v126, v127
	ds_read_b128 v[48:51], v10 offset:1536
	v_add_f32_dpp v130, v128, v128 row_mirror row_mask:0xf bank_mask:0xf bound_ctrl:1
	v_pk_fma_f32 v[12:13], v[76:77], v[130:131], v[122:123] op_sel_hi:[1,0,1]
	v_pk_fma_f32 v[14:15], v[78:79], v[130:131], v[124:125] op_sel_hi:[1,0,1]
	v_pk_mul_f32 v[126:127], v[12:13], v[84:85]
	v_pk_fma_f32 v[126:127], v[14:15], v[86:87], v[126:127]
	s_waitcnt lgkmcnt(5)
	ds_read_b128 v[72:75], v10 offset:9984
	v_pk_mul_f32 v[120:121], v[12:13], v[152:153]
	v_pk_fma_f32 v[120:121], v[14:15], v[154:155], v[120:121]
	v_pk_mul_f32 v[122:123], v[12:13], v[144:145]
	v_add_f32_e32 v128, v120, v121
	v_pk_mul_f32 v[124:125], v[14:15], v[146:147]
	v_pk_fma_f32 v[122:123], v[148:149], v[92:93], v[122:123] op_sel:[0,1,0] op_sel_hi:[1,1,1]
	v_add_f32_dpp v128, v128, v128 quad_perm:[1,0,3,2] row_mask:0xf bank_mask:0xf bound_ctrl:1
	v_pk_fma_f32 v[124:125], v[150:151], v[92:93], v[124:125] op_sel:[0,1,0] op_sel_hi:[1,1,1]
	ds_read_b128 v[68:71], v10 offset:5888
	v_add_f32_dpp v128, v128, v128 quad_perm:[2,3,0,1] row_mask:0xf bank_mask:0xf bound_ctrl:1
	ds_read_b128 v[76:79], v10 offset:14080
	ds_read_b128 v[84:87], v10 offset:18176
	v_add_f32_dpp v128, v128, v128 row_half_mirror row_mask:0xf bank_mask:0xf bound_ctrl:1
	v_add_f32_e32 v108, v126, v127
	ds_read_b128 v[64:67], v10 offset:1792
	v_add_f32_dpp v130, v128, v128 row_mirror row_mask:0xf bank_mask:0xf bound_ctrl:1
	v_pk_fma_f32 v[12:13], v[156:157], v[130:131], v[122:123] op_sel_hi:[1,0,1]
	v_pk_fma_f32 v[14:15], v[158:159], v[130:131], v[124:125] op_sel_hi:[1,0,1]
	v_pk_mul_f32 v[126:127], v[12:13], v[138:139]
	v_pk_fma_f32 v[126:127], v[14:15], v[140:141], v[126:127]
	s_waitcnt lgkmcnt(5)
	ds_read_b128 v[152:155], v10 offset:10240
	v_pk_mul_f32 v[120:121], v[12:13], v[56:57]
	v_pk_fma_f32 v[120:121], v[14:15], v[58:59], v[120:121]
	v_pk_mul_f32 v[122:123], v[12:13], v[48:49]
	v_add_f32_e32 v128, v120, v121
	v_pk_mul_f32 v[124:125], v[14:15], v[50:51]
	v_pk_fma_f32 v[122:123], v[52:53], v[94:95], v[122:123] op_sel_hi:[1,0,1]
	v_add_f32_dpp v128, v128, v128 quad_perm:[1,0,3,2] row_mask:0xf bank_mask:0xf bound_ctrl:1
	v_pk_fma_f32 v[124:125], v[54:55], v[94:95], v[124:125] op_sel_hi:[1,0,1]
	ds_read_b128 v[148:151], v10 offset:6144
	v_add_f32_dpp v128, v128, v128 quad_perm:[2,3,0,1] row_mask:0xf bank_mask:0xf bound_ctrl:1
	ds_read_b128 v[156:159], v10 offset:14336
	ds_read_b128 v[138:141], v10 offset:18432
	v_add_f32_dpp v128, v128, v128 row_half_mirror row_mask:0xf bank_mask:0xf bound_ctrl:1
	v_add_f32_e32 v109, v126, v127
	ds_read_b128 v[144:147], v10 offset:2048
	v_add_f32_dpp v130, v128, v128 row_mirror row_mask:0xf bank_mask:0xf bound_ctrl:1
	v_pk_fma_f32 v[12:13], v[60:61], v[130:131], v[122:123] op_sel_hi:[1,0,1]
	v_pk_fma_f32 v[14:15], v[62:63], v[130:131], v[124:125] op_sel_hi:[1,0,1]
	v_pk_mul_f32 v[126:127], v[12:13], v[80:81]
	v_pk_fma_f32 v[126:127], v[14:15], v[82:83], v[126:127]
	s_waitcnt lgkmcnt(5)
	ds_read_b128 v[56:59], v10 offset:10496
	v_pk_mul_f32 v[120:121], v[12:13], v[72:73]
	v_pk_fma_f32 v[120:121], v[14:15], v[74:75], v[120:121]
	v_pk_mul_f32 v[122:123], v[12:13], v[64:65]
	v_add_f32_e32 v128, v120, v121
	v_pk_mul_f32 v[124:125], v[14:15], v[66:67]
	v_pk_fma_f32 v[122:123], v[68:69], v[94:95], v[122:123] op_sel:[0,1,0] op_sel_hi:[1,1,1]
	v_add_f32_dpp v128, v128, v128 quad_perm:[1,0,3,2] row_mask:0xf bank_mask:0xf bound_ctrl:1
	v_pk_fma_f32 v[124:125], v[70:71], v[94:95], v[124:125] op_sel:[0,1,0] op_sel_hi:[1,1,1]
	ds_read_b128 v[52:55], v10 offset:6400
	v_add_f32_dpp v128, v128, v128 quad_perm:[2,3,0,1] row_mask:0xf bank_mask:0xf bound_ctrl:1
	ds_read_b128 v[60:63], v10 offset:14592
	ds_read_b128 v[80:83], v10 offset:18688
	v_add_f32_dpp v128, v128, v128 row_half_mirror row_mask:0xf bank_mask:0xf bound_ctrl:1
	v_add_f32_e32 v110, v126, v127
	ds_read_b128 v[48:51], v10 offset:2304
	v_add_f32_dpp v130, v128, v128 row_mirror row_mask:0xf bank_mask:0xf bound_ctrl:1
	v_pk_fma_f32 v[12:13], v[76:77], v[130:131], v[122:123] op_sel_hi:[1,0,1]
	v_pk_fma_f32 v[14:15], v[78:79], v[130:131], v[124:125] op_sel_hi:[1,0,1]
	v_pk_mul_f32 v[126:127], v[12:13], v[84:85]
	v_pk_fma_f32 v[126:127], v[14:15], v[86:87], v[126:127]
	s_waitcnt lgkmcnt(5)
; __device__ __forceinline__ void rwkv_item(const Params& p, int item, float* sm) {
;     ...
; #pragma unroll
;       for (int t = 0; t < TC; t++) {
;         const float4 w4 = *(const float4*)(bw + 0 * TC * 64 + t * 64 + sub * 4);
;         const float4 k4 = *(const float4*)(bw + 1 * TC * 64 + t * 64 + sub * 4);
;         const float4 a4 = *(const float4*)(bw + 2 * TC * 64 + t * 64 + sub * 4);
;         const float4 b4 = *(const float4*)(bw + 3 * TC * 64 + t * 64 + sub * 4);
;         const float4 r4 = *(const float4*)(bw + 4 * TC * 64 + t * 64 + sub * 4);
;         const float v = bv[t * 16 + rowl];
;         const float sa = dpp_sum16((S0 * a4.x + S1 * a4.y) + (S2 * a4.z + S3 * a4.w));
;         S0 = (S0 * w4.x + v * k4.x) + sa * b4.x;
;         S1 = (S1 * w4.y + v * k4.y) + sa * b4.y;
;         S2 = (S2 * w4.z + v * k4.z) + sa * b4.z;
;         S3 = (S3 * w4.w + v * k4.w) + sa * b4.w;
;         yreg[t] = (S0 * r4.x + S1 * r4.y) + (S2 * r4.z + S3 * r4.w);
;       }
	ds_read_b128 v[72:75], v10 offset:10752
	v_pk_mul_f32 v[120:121], v[12:13], v[152:153]
	v_pk_fma_f32 v[120:121], v[14:15], v[154:155], v[120:121]
	v_pk_mul_f32 v[122:123], v[12:13], v[144:145]
	v_add_f32_e32 v128, v120, v121
	v_pk_mul_f32 v[124:125], v[14:15], v[146:147]
	v_pk_fma_f32 v[122:123], v[148:149], v[96:97], v[122:123] op_sel_hi:[1,0,1]
	v_add_f32_dpp v128, v128, v128 quad_perm:[1,0,3,2] row_mask:0xf bank_mask:0xf bound_ctrl:1
	v_pk_fma_f32 v[124:125], v[150:151], v[96:97], v[124:125] op_sel_hi:[1,0,1]
	ds_read_b128 v[68:71], v10 offset:6656
	v_add_f32_dpp v128, v128, v128 quad_perm:[2,3,0,1] row_mask:0xf bank_mask:0xf bound_ctrl:1
	ds_read_b128 v[76:79], v10 offset:14848
	ds_read_b128 v[84:87], v10 offset:18944
	v_add_f32_dpp v128, v128, v128 row_half_mirror row_mask:0xf bank_mask:0xf bound_ctrl:1
	v_add_f32_e32 v111, v126, v127
	ds_read_b128 v[64:67], v10 offset:2560
	v_add_f32_dpp v130, v128, v128 row_mirror row_mask:0xf bank_mask:0xf bound_ctrl:1
	v_pk_fma_f32 v[12:13], v[156:157], v[130:131], v[122:123] op_sel_hi:[1,0,1]
	v_pk_fma_f32 v[14:15], v[158:159], v[130:131], v[124:125] op_sel_hi:[1,0,1]
	v_pk_mul_f32 v[126:127], v[12:13], v[138:139]
	v_pk_fma_f32 v[126:127], v[14:15], v[140:141], v[126:127]
	s_waitcnt lgkmcnt(5)
	ds_read_b128 v[152:155], v10 offset:11008
	v_pk_mul_f32 v[120:121], v[12:13], v[56:57]
	v_pk_fma_f32 v[120:121], v[14:15], v[58:59], v[120:121]
	v_pk_mul_f32 v[122:123], v[12:13], v[48:49]
	v_add_f32_e32 v128, v120, v121
	v_pk_mul_f32 v[124:125], v[14:15], v[50:51]
	v_pk_fma_f32 v[122:123], v[52:53], v[96:97], v[122:123] op_sel:[0,1,0] op_sel_hi:[1,1,1]
	v_add_f32_dpp v128, v128, v128 quad_perm:[1,0,3,2] row_mask:0xf bank_mask:0xf bound_ctrl:1
	v_pk_fma_f32 v[124:125], v[54:55], v[96:97], v[124:125] op_sel:[0,1,0] op_sel_hi:[1,1,1]
	ds_read_b128 v[148:151], v10 offset:6912
	v_add_f32_dpp v128, v128, v128 quad_perm:[2,3,0,1] row_mask:0xf bank_mask:0xf bound_ctrl:1
	ds_read_b128 v[156:159], v10 offset:15104
	ds_read_b128 v[138:141], v10 offset:19200
	v_add_f32_dpp v128, v128, v128 row_half_mirror row_mask:0xf bank_mask:0xf bound_ctrl:1
	v_add_f32_e32 v112, v126, v127
	ds_read_b128 v[144:147], v10 offset:2816
	v_add_f32_dpp v130, v128, v128 row_mirror row_mask:0xf bank_mask:0xf bound_ctrl:1
	v_pk_fma_f32 v[12:13], v[60:61], v[130:131], v[122:123] op_sel_hi:[1,0,1]
	v_pk_fma_f32 v[14:15], v[62:63], v[130:131], v[124:125] op_sel_hi:[1,0,1]
	v_pk_mul_f32 v[126:127], v[12:13], v[80:81]
	v_pk_fma_f32 v[126:127], v[14:15], v[82:83], v[126:127]
	s_waitcnt lgkmcnt(5)
	ds_read_b128 v[56:59], v10 offset:11264
	v_pk_mul_f32 v[120:121], v[12:13], v[72:73]
	v_pk_fma_f32 v[120:121], v[14:15], v[74:75], v[120:121]
	v_pk_mul_f32 v[122:123], v[12:13], v[64:65]
	v_add_f32_e32 v128, v120, v121
	v_pk_mul_f32 v[124:125], v[14:15], v[66:67]
	v_pk_fma_f32 v[122:123], v[68:69], v[98:99], v[122:123] op_sel_hi:[1,0,1]
	v_add_f32_dpp v128, v128, v128 quad_perm:[1,0,3,2] row_mask:0xf bank_mask:0xf bound_ctrl:1
	v_pk_fma_f32 v[124:125], v[70:71], v[98:99], v[124:125] op_sel_hi:[1,0,1]
	ds_read_b128 v[52:55], v10 offset:7168
	v_add_f32_dpp v128, v128, v128 quad_perm:[2,3,0,1] row_mask:0xf bank_mask:0xf bound_ctrl:1
	ds_read_b128 v[60:63], v10 offset:15360
	ds_read_b128 v[80:83], v10 offset:19456
	v_add_f32_dpp v128, v128, v128 row_half_mirror row_mask:0xf bank_mask:0xf bound_ctrl:1
	v_add_f32_e32 v113, v126, v127
	ds_read_b128 v[48:51], v10 offset:3072
	v_add_f32_dpp v130, v128, v128 row_mirror row_mask:0xf bank_mask:0xf bound_ctrl:1
	v_pk_fma_f32 v[12:13], v[76:77], v[130:131], v[122:123] op_sel_hi:[1,0,1]
	v_pk_fma_f32 v[14:15], v[78:79], v[130:131], v[124:125] op_sel_hi:[1,0,1]
	v_pk_mul_f32 v[126:127], v[12:13], v[84:85]
	v_pk_fma_f32 v[126:127], v[14:15], v[86:87], v[126:127]
	s_waitcnt lgkmcnt(5)
	ds_read_b128 v[72:75], v10 offset:11520
	v_pk_mul_f32 v[120:121], v[12:13], v[152:153]
	v_pk_fma_f32 v[120:121], v[14:15], v[154:155], v[120:121]
	v_pk_mul_f32 v[122:123], v[12:13], v[144:145]
	v_add_f32_e32 v128, v120, v121
	v_pk_mul_f32 v[124:125], v[14:15], v[146:147]
	v_pk_fma_f32 v[122:123], v[148:149], v[98:99], v[122:123] op_sel:[0,1,0] op_sel_hi:[1,1,1]
	v_add_f32_dpp v128, v128, v128 quad_perm:[1,0,3,2] row_mask:0xf bank_mask:0xf bound_ctrl:1
	v_pk_fma_f32 v[124:125], v[150:151], v[98:99], v[124:125] op_sel:[0,1,0] op_sel_hi:[1,1,1]
	ds_read_b128 v[68:71], v10 offset:7424
	v_add_f32_dpp v128, v128, v128 quad_perm:[2,3,0,1] row_mask:0xf bank_mask:0xf bound_ctrl:1
	ds_read_b128 v[76:79], v10 offset:15616
	ds_read_b128 v[84:87], v10 offset:19712
	v_add_f32_dpp v128, v128, v128 row_half_mirror row_mask:0xf bank_mask:0xf bound_ctrl:1
	v_add_f32_e32 v114, v126, v127
	ds_read_b128 v[64:67], v10 offset:3328
	v_add_f32_dpp v130, v128, v128 row_mirror row_mask:0xf bank_mask:0xf bound_ctrl:1
	v_pk_fma_f32 v[12:13], v[156:157], v[130:131], v[122:123] op_sel_hi:[1,0,1]
	v_pk_fma_f32 v[14:15], v[158:159], v[130:131], v[124:125] op_sel_hi:[1,0,1]
	v_pk_mul_f32 v[126:127], v[12:13], v[138:139]
	v_pk_fma_f32 v[126:127], v[14:15], v[140:141], v[126:127]
	s_waitcnt lgkmcnt(5)
; __device__ __forceinline__ void rwkv_item(const Params& p, int item, float* sm) {
;     ...
; #pragma unroll
;       for (int t = 0; t < TC; t++) {
;         const float4 w4 = *(const float4*)(bw + 0 * TC * 64 + t * 64 + sub * 4);
;         const float4 k4 = *(const float4*)(bw + 1 * TC * 64 + t * 64 + sub * 4);
;         const float4 a4 = *(const float4*)(bw + 2 * TC * 64 + t * 64 + sub * 4);
;         const float4 b4 = *(const float4*)(bw + 3 * TC * 64 + t * 64 + sub * 4);
;         const float4 r4 = *(const float4*)(bw + 4 * TC * 64 + t * 64 + sub * 4);
;         const float v = bv[t * 16 + rowl];
;         const float sa = dpp_sum16((S0 * a4.x + S1 * a4.y) + (S2 * a4.z + S3 * a4.w));
;         S0 = (S0 * w4.x + v * k4.x) + sa * b4.x;
;         S1 = (S1 * w4.y + v * k4.y) + sa * b4.y;
;         S2 = (S2 * w4.z + v * k4.z) + sa * b4.z;
;         S3 = (S3 * w4.w + v * k4.w) + sa * b4.w;
;         yreg[t] = (S0 * r4.x + S1 * r4.y) + (S2 * r4.z + S3 * r4.w);
;       }
; #pragma unroll
;       for (int t = 0; t < TC; t++) yreg[t] = dpp_sum16(yreg[t]);
;       if (sub == 0) {
; #pragma unroll
;         for (int t = 0; t < TC; t++) by[t * 16 + rowl] = yreg[t];
;       }
	ds_read_b128 v[152:155], v10 offset:11776
	v_pk_mul_f32 v[120:121], v[12:13], v[56:57]
	v_pk_fma_f32 v[120:121], v[14:15], v[58:59], v[120:121]
	v_pk_mul_f32 v[122:123], v[12:13], v[48:49]
	v_add_f32_e32 v128, v120, v121
	v_pk_mul_f32 v[124:125], v[14:15], v[50:51]
	v_pk_fma_f32 v[122:123], v[52:53], v[100:101], v[122:123] op_sel_hi:[1,0,1]
	v_add_f32_dpp v128, v128, v128 quad_perm:[1,0,3,2] row_mask:0xf bank_mask:0xf bound_ctrl:1
	v_pk_fma_f32 v[124:125], v[54:55], v[100:101], v[124:125] op_sel_hi:[1,0,1]
	ds_read_b128 v[148:151], v10 offset:7680
	v_add_f32_dpp v128, v128, v128 quad_perm:[2,3,0,1] row_mask:0xf bank_mask:0xf bound_ctrl:1
	ds_read_b128 v[156:159], v10 offset:15872
	ds_read_b128 v[138:141], v10 offset:19968
	v_add_f32_dpp v128, v128, v128 row_half_mirror row_mask:0xf bank_mask:0xf bound_ctrl:1
	v_add_f32_e32 v115, v126, v127
	ds_read_b128 v[144:147], v10 offset:3584
	v_add_f32_dpp v130, v128, v128 row_mirror row_mask:0xf bank_mask:0xf bound_ctrl:1
	v_pk_fma_f32 v[12:13], v[60:61], v[130:131], v[122:123] op_sel_hi:[1,0,1]
	v_pk_fma_f32 v[14:15], v[62:63], v[130:131], v[124:125] op_sel_hi:[1,0,1]
	v_pk_mul_f32 v[126:127], v[12:13], v[80:81]
	v_pk_fma_f32 v[126:127], v[14:15], v[82:83], v[126:127]
	s_waitcnt lgkmcnt(5)
	ds_read_b128 v[56:59], v10 offset:12032
	v_pk_mul_f32 v[120:121], v[12:13], v[72:73]
	v_pk_fma_f32 v[120:121], v[14:15], v[74:75], v[120:121]
	v_pk_mul_f32 v[122:123], v[12:13], v[64:65]
	v_add_f32_e32 v128, v120, v121
	v_pk_mul_f32 v[124:125], v[14:15], v[66:67]
	v_pk_fma_f32 v[122:123], v[68:69], v[100:101], v[122:123] op_sel:[0,1,0] op_sel_hi:[1,1,1]
	v_add_f32_dpp v128, v128, v128 quad_perm:[1,0,3,2] row_mask:0xf bank_mask:0xf bound_ctrl:1
	v_pk_fma_f32 v[124:125], v[70:71], v[100:101], v[124:125] op_sel:[0,1,0] op_sel_hi:[1,1,1]
	ds_read_b128 v[52:55], v10 offset:7936
	v_add_f32_dpp v128, v128, v128 quad_perm:[2,3,0,1] row_mask:0xf bank_mask:0xf bound_ctrl:1
	ds_read_b128 v[60:63], v10 offset:16128
	ds_read_b128 v[80:83], v10 offset:20224
	v_add_f32_dpp v128, v128, v128 row_half_mirror row_mask:0xf bank_mask:0xf bound_ctrl:1
	v_add_f32_e32 v116, v126, v127
	ds_read_b128 v[48:51], v10 offset:3840
	v_add_f32_dpp v130, v128, v128 row_mirror row_mask:0xf bank_mask:0xf bound_ctrl:1
	v_pk_fma_f32 v[12:13], v[76:77], v[130:131], v[122:123] op_sel_hi:[1,0,1]
	v_pk_fma_f32 v[14:15], v[78:79], v[130:131], v[124:125] op_sel_hi:[1,0,1]
	v_pk_mul_f32 v[126:127], v[12:13], v[84:85]
	v_pk_fma_f32 v[126:127], v[14:15], v[86:87], v[126:127]
	s_waitcnt lgkmcnt(5)
	v_pk_mul_f32 v[120:121], v[12:13], v[152:153]
	v_pk_fma_f32 v[120:121], v[14:15], v[154:155], v[120:121]
	v_pk_mul_f32 v[122:123], v[12:13], v[144:145]
	v_add_f32_e32 v128, v120, v121
	v_pk_mul_f32 v[124:125], v[14:15], v[146:147]
	v_pk_fma_f32 v[122:123], v[148:149], v[102:103], v[122:123] op_sel_hi:[1,0,1]
	v_add_f32_dpp v128, v128, v128 quad_perm:[1,0,3,2] row_mask:0xf bank_mask:0xf bound_ctrl:1
	v_pk_fma_f32 v[124:125], v[150:151], v[102:103], v[124:125] op_sel_hi:[1,0,1]
	s_nop 0
	v_add_f32_dpp v128, v128, v128 quad_perm:[2,3,0,1] row_mask:0xf bank_mask:0xf bound_ctrl:1
	s_nop 1
	v_add_f32_dpp v128, v128, v128 row_half_mirror row_mask:0xf bank_mask:0xf bound_ctrl:1
	v_add_f32_e32 v117, v126, v127
	s_nop 0
	v_add_f32_dpp v130, v128, v128 row_mirror row_mask:0xf bank_mask:0xf bound_ctrl:1
	v_pk_fma_f32 v[12:13], v[156:157], v[130:131], v[122:123] op_sel_hi:[1,0,1]
	v_pk_fma_f32 v[14:15], v[158:159], v[130:131], v[124:125] op_sel_hi:[1,0,1]
	v_pk_mul_f32 v[126:127], v[12:13], v[138:139]
	v_pk_fma_f32 v[126:127], v[14:15], v[140:141], v[126:127]
	s_waitcnt lgkmcnt(0)
	v_pk_mul_f32 v[120:121], v[12:13], v[56:57]
	v_pk_fma_f32 v[120:121], v[14:15], v[58:59], v[120:121]
	v_pk_mul_f32 v[122:123], v[12:13], v[48:49]
	v_add_f32_e32 v128, v120, v121
	v_pk_mul_f32 v[124:125], v[14:15], v[50:51]
	v_pk_fma_f32 v[122:123], v[52:53], v[102:103], v[122:123] op_sel:[0,1,0] op_sel_hi:[1,1,1]
	v_add_f32_dpp v128, v128, v128 quad_perm:[1,0,3,2] row_mask:0xf bank_mask:0xf bound_ctrl:1
	v_pk_fma_f32 v[124:125], v[54:55], v[102:103], v[124:125] op_sel:[0,1,0] op_sel_hi:[1,1,1]
	s_nop 0
	v_add_f32_dpp v128, v128, v128 quad_perm:[2,3,0,1] row_mask:0xf bank_mask:0xf bound_ctrl:1
	s_nop 1
	v_add_f32_dpp v128, v128, v128 row_half_mirror row_mask:0xf bank_mask:0xf bound_ctrl:1
	v_add_f32_e32 v118, v126, v127
	s_nop 0
	v_add_f32_dpp v130, v128, v128 row_mirror row_mask:0xf bank_mask:0xf bound_ctrl:1
	v_pk_fma_f32 v[12:13], v[60:61], v[130:131], v[122:123] op_sel_hi:[1,0,1]
	v_pk_fma_f32 v[14:15], v[62:63], v[130:131], v[124:125] op_sel_hi:[1,0,1]
	v_pk_mul_f32 v[126:127], v[12:13], v[80:81]
	v_pk_fma_f32 v[126:127], v[14:15], v[82:83], v[126:127]
	v_add_f32_e32 v119, v126, v127
	s_xor_b32 s29, s1, 0x5800
	v_add_u32_e32 v43, s29, v132
	v_add_u32_e32 v44, s29, v133
	ds_write_b128 v134, v[104:107]
	ds_write_b128 v134, v[108:111] offset:16
	ds_write_b128 v134, v[112:115] offset:32
	ds_write_b128 v134, v[116:119] offset:48
	s_cmp_eq_u32 s0, 512
	s_cbranch_scc1 .Lrw_noprep
	s_waitcnt vmcnt(0)
	v_lshlrev_b32_e32 v48, 16, v34
	v_and_b32_e32 v49, 0xffff0000, v34
	v_lshlrev_b32_e32 v50, 16, v35
	v_and_b32_e32 v51, 0xffff0000, v35
	v_lshlrev_b32_e32 v52, 16, v36
	v_and_b32_e32 v53, 0xffff0000, v36
	v_lshlrev_b32_e32 v54, 16, v37
	v_and_b32_e32 v55, 0xffff0000, v37
	v_lshlrev_b32_e32 v56, 16, v38
	v_and_b32_e32 v57, 0xffff0000, v38
	v_lshlrev_b32_e32 v58, 16, v39
	v_and_b32_e32 v59, 0xffff0000, v39
	v_lshlrev_b32_e32 v60, 16, v40
	v_and_b32_e32 v61, 0xffff0000, v40
	v_lshlrev_b32_e32 v62, 16, v41
	v_and_b32_e32 v63, 0xffff0000, v41
	v_lshlrev_b32_e32 v64, 16, v42
	v_pk_mul_f32 v[68:69], v[52:53], v[16:17]
	v_pk_mul_f32 v[70:71], v[54:55], v[18:19]
	v_pk_mul_f32 v[72:73], v[68:69], v[68:69]
	v_pk_fma_f32 v[72:73], v[70:71], v[70:71], v[72:73]
	v_pk_add_f32 v[76:77], v[56:57], s[20:21]
	v_add_f32_e32 v74, v72, v73
	v_pk_add_f32 v[78:79], v[58:59], s[20:21]
	v_pk_mul_f32 v[84:85], v[60:61], s[22:23]
	v_add_f32_dpp v74, v74, v74 quad_perm:[1,0,3,2] row_mask:0xf bank_mask:0xf bound_ctrl:1
	v_pk_mul_f32 v[86:87], v[62:63], s[22:23]
	v_pk_fma_f32 v[76:77], v[76:77], v[20:21], s[30:31]
	v_add_f32_dpp v74, v74, v74 quad_perm:[2,3,0,1] row_mask:0xf bank_mask:0xf bound_ctrl:1
	v_pk_fma_f32 v[78:79], v[78:79], v[22:23], s[30:31]
	v_exp_f32_e32 v84, v84
	v_add_f32_dpp v74, v74, v74 row_half_mirror row_mask:0xf bank_mask:0xf bound_ctrl:1
	v_exp_f32_e32 v85, v85
	v_exp_f32_e32 v86, v86
	v_add_f32_dpp v74, v74, v74 row_mirror row_mask:0xf bank_mask:0xf bound_ctrl:1
	v_exp_f32_e32 v87, v87
	v_pk_mul_f32 v[80:81], v[52:53], v[76:77]
	v_add_f32_e32 v74, 0x358637bd, v74
	v_pk_mul_f32 v[82:83], v[54:55], v[78:79]
	v_rsq_f32_e32 v120, v74
	ds_write_b128 v43, v[84:87]
	ds_write_b128 v43, v[48:51] offset:16384
	ds_write_b32 v44, v64
	ds_write_b128 v43, v[80:83] offset:4096
	v_pk_mul_f32 v[124:125], v[68:69], v[120:121] op_sel_hi:[1,0] neg_lo:[0,1] neg_hi:[0,1]
	v_pk_mul_f32 v[126:127], v[70:71], v[120:121] op_sel_hi:[1,0] neg_lo:[0,1] neg_hi:[0,1]
	v_pk_mul_f32 v[100:101], v[124:125], v[56:57] neg_lo:[1,0] neg_hi:[1,0]
	v_pk_mul_f32 v[102:103], v[126:127], v[58:59] neg_lo:[1,0] neg_hi:[1,0]
	ds_write_b128 v43, v[124:127] offset:8192
	ds_write_b128 v43, v[100:103] offset:12288
	s_cmp_lg_u32 s18, 0
	s_cbranch_scc1 .Lrw_nosb_p1
	v_pk_mul_f32 v[104:105], v[48:49], v[80:81]
	v_pk_mul_f32 v[106:107], v[50:51], v[82:83]
	v_pk_mul_f32 v[108:109], v[104:105], v[24:25]
	v_pk_fma_f32 v[108:109], v[106:107], v[26:27], v[108:109]
	v_add_f32_e32 v110, v108, v109
	s_nop 1
	v_add_f32_dpp v110, v110, v110 quad_perm:[1,0,3,2] row_mask:0xf bank_mask:0xf bound_ctrl:1
	s_nop 1
	v_add_f32_dpp v110, v110, v110 quad_perm:[2,3,0,1] row_mask:0xf bank_mask:0xf bound_ctrl:1
	s_nop 1
	v_add_f32_dpp v110, v110, v110 row_half_mirror row_mask:0xf bank_mask:0xf bound_ctrl:1
	s_nop 1
	v_add_f32_dpp v110, v110, v110 row_mirror row_mask:0xf bank_mask:0xf bound_ctrl:1
	global_store_dword v33, v110, s[16:17]

; __device__ __forceinline__ void rwkv_item(const Params& p, int item, float* sm) {
;     ...
;     __syncthreads();
;     {
;       const float* bb = sm + bi * BUF;
;       const float yv = bb[5 * TC * 64 + TC * 16 + TC + ltt * 16 + lrr];
;       const float mu = dpp_sum16(yv) * (1.f / 16.f);
;       yr[(size_t)(t0 + ltt) * D + h * 64 + rg * 16 + lrr] = f2bf(yv - mu);
;       if (lrr == 0) MU[(rowb + t0 + ltt) * 64 + h * 4 + rg] = mu;
;     }
;   }
.Lrw_noprep:
	v_add_u32_e32 v10, s29, v47
	v_add_u32_e32 v11, s29, v136
	s_waitcnt lgkmcnt(0)
	s_barrier
	ds_read_b32 v104, v135
	ds_read_b32 v105, v135 offset:64
	ds_read_b32 v106, v135 offset:128
	ds_read_b32 v107, v135 offset:192
	ds_read_b32 v108, v135 offset:256
	ds_read_b32 v109, v135 offset:320
	ds_read_b32 v110, v135 offset:384
	ds_read_b32 v111, v135 offset:448
	ds_read_b32 v112, v135 offset:512
	ds_read_b32 v113, v135 offset:576
	ds_read_b32 v114, v135 offset:640
	ds_read_b32 v115, v135 offset:704
	ds_read_b32 v116, v135 offset:768
	ds_read_b32 v117, v135 offset:832
	ds_read_b32 v118, v135 offset:896
	ds_read_b32 v119, v135 offset:960
	ds_read_b128 v[56:59], v10 offset:8192
	ds_read_b128 v[48:51], v10
	ds_read_b128 v[52:55], v10 offset:4096
	ds_read_b128 v[60:63], v10 offset:12288
	ds_read_b128 v[80:83], v10 offset:16384
	ds_read_b128 v[88:91], v11 offset:0
	ds_read_b128 v[92:95], v11 offset:16
	ds_read_b128 v[96:99], v11 offset:32
	ds_read_b128 v[100:103], v11 offset:48
	ds_read_b128 v[72:75], v10 offset:8448
	ds_read_b128 v[64:67], v10 offset:256
	ds_read_b128 v[68:71], v10 offset:4352
	ds_read_b128 v[76:79], v10 offset:12544
	ds_read_b128 v[84:87], v10 offset:16640
	s_waitcnt lgkmcnt(14)
	v_add_f32_e32 v104, v104, v112
	v_add_f32_e32 v105, v105, v113
	v_add_f32_e32 v106, v106, v114
	v_add_f32_e32 v107, v107, v115
	v_add_f32_e32 v108, v108, v116
	v_add_f32_e32 v109, v109, v117
	v_add_f32_e32 v110, v110, v118
	v_add_f32_e32 v111, v111, v119
	v_add_f32_e32 v104, v104, v108
	v_add_f32_e32 v105, v105, v109
	v_add_f32_e32 v106, v106, v110
	v_add_f32_e32 v107, v107, v111
	v_add_f32_e32 v104, v104, v106
	v_add_f32_e32 v105, v105, v107
	v_add_f32_e32 v120, v104, v105
	s_nop 1
	v_add_f32_dpp v122, v120, v120 quad_perm:[1,0,3,2] row_mask:0xf bank_mask:0xf bound_ctrl:1
	s_nop 1
	v_add_f32_dpp v122, v122, v122 quad_perm:[2,3,0,1] row_mask:0xf bank_mask:0xf bound_ctrl:1
	s_nop 1
	v_add_f32_dpp v122, v122, v122 row_half_mirror row_mask:0xf bank_mask:0xf bound_ctrl:1
	s_nop 1
	v_add_f32_dpp v122, v122, v122 row_mirror row_mask:0xf bank_mask:0xf bound_ctrl:1
	s_nop 0
	v_fmac_f32_e32 v120, 0xbd800000, v122
	v_mul_f32_e32 v122, 0x3d800000, v122
	v_cvt_pk_bf16_f32 v124, v120, v120
	global_store_dword v32, v122, s[14:15]
	global_store_short v31, v124, s[10:11]
	s_add_u32 s10, s10, 0x8000
	s_addc_u32 s11, s11, 0
	s_add_u32 s14, s14, 0x1000
	s_addc_u32 s15, s15, 0
	s_mov_b32 s1, s29
	s_add_i32 s0, s0, 1
	s_cmp_lg_u32 s0, 513
	s_cbranch_scc1 .Lrw_chunk
	s_waitcnt lgkmcnt(0)
	s_branch .LBB0_504
